# q_b GEMM: the peeled first K-iteration of a non-first tile waits with vmcnt(24) so it does not wait for the previous tile's 16 output stores
# speedup vs baseline: 1.0055x; 1.0022x over previous
.LBB0_599:
	s_mov_b32 s101, 0
	s_movk_i32 s0, 0x180
	v_mov_b32_e32 v18, v196
	s_cmpk_gt_i32 s33, 0x17f
	s_nop 0
	v_readfirstlane_b32 s6, v18
	s_cbranch_scc1 .LBB0_620
	v_lshlrev_b32_e32 v0, 4, v18
	v_add_u32_e32 v1, 0x2000, v0
	v_ashrrev_i32_e32 v2, 31, v1
	v_lshrrev_b32_e32 v2, 22, v2
	v_add_u32_e32 v2, v1, v2
	v_ashrrev_i32_e32 v2, 10, v2
	v_mul_i32_i24_e32 v3, 0x400, v2
	v_sub_u32_e32 v1, v1, v3
	v_lshrrev_b32_e32 v3, 4, v1
	v_bitop3_b32 v1, v3, v1, 32 bitop3:0x6c
	s_ashr_i32 s7, s6, 6
	s_ashr_i32 s1, s0, 31
	v_ashrrev_i32_e32 v3, 31, v1
	s_ashr_i32 s54, s6, 8
	s_lshl_b64 s[10:11], s[0:1], 8
	s_lshl_b64 s[62:63], s[0:1], 9
	s_lshl_b32 s8, s7, 10
	v_lshrrev_b32_e32 v3, 26, v3
	s_add_u32 s9, s68, 0x6760000
	v_add_u32_e32 v3, v1, v3
	v_lshlrev_b32_e32 v5, 3, v2
	s_addc_u32 s15, s69, 0
	v_ashrrev_i32_e32 v4, 6, v3
	v_and_b32_e32 v5, -16, v5
	v_lshlrev_b32_e32 v2, 5, v2
	v_add_u32_e32 v5, v4, v5
	v_and_b32_e32 v12, 32, v2
	v_and_b32_e32 v2, 0xc0, v3
	s_and_b64 s[4:5], s[4:5], exec
	v_and_b32_e32 v4, 3, v4
	s_mov_b32 s46, 0x7fffffe0
	v_lshrrev_b32_e32 v6, 2, v5
	v_lshlrev_b32_e32 v7, 1, v5
	v_sub_u32_e32 v1, v1, v2
	v_mov_b32_e32 v2, 1
	s_cselect_b32 s4, 49, 48
	v_and_or_b32 v4, v5, s46, v4
	v_and_b32_e32 v6, 4, v6
	v_and_b32_e32 v7, 24, v7
	v_ashrrev_i16_sdwa v1, v2, sext(v1) dst_sel:DWORD dst_unused:UNUSED_PAD src0_sel:DWORD src1_sel:BYTE_0
	s_mul_i32 s4, s14, s4
	v_or3_b32 v4, v4, v6, v7
	v_bfe_i32 v13, v1, 0, 16
	s_add_i32 s4, s4, s3
	v_mul_lo_u32 v4, v4, s0
	v_add_u32_e32 v1, v12, v13
	v_mul_lo_u32 v14, v5, s0
	s_mul_hi_i32 s3, s4, 0x2aaaaaab
	v_add_lshl_u32 v128, v4, v1, 1
	v_add_lshl_u32 v130, v1, v14, 1
	v_bfe_i32 v1, v18, 27, 1
	s_lshr_b32 s5, s3, 31
	s_ashr_i32 s3, s3, 3
	v_lshrrev_b32_e32 v1, 22, v1
	s_add_i32 s3, s3, s5
	v_add_u32_e32 v1, v0, v1
	s_lshl_b32 s5, s3, 3
	s_mul_i32 s3, s3, 48
	v_and_b32_e32 v1, 0xfffffc00, v1
	s_sub_i32 s3, s4, s3
	v_sub_u32_e32 v0, v0, v1
	s_bfe_i32 s4, s3, 0x80000
	v_lshrrev_b32_e32 v1, 4, v0
	v_ashrrev_i32_e32 v4, 31, v18
	s_bfe_u32 s4, s4, 0x3000c
	v_bitop3_b32 v0, v1, v0, 32 bitop3:0x6c
	v_lshrrev_b32_e32 v4, 26, v4
	s_add_i32 s14, s3, s4
	v_ashrrev_i32_e32 v1, 31, v0
	v_add_u32_e32 v4, v18, v4
	s_bfe_i32 s4, s14, 0x80000
	s_and_b32 s14, s14, 0xf8
	v_lshrrev_b32_e32 v1, 26, v1
	v_ashrrev_i32_e32 v4, 6, v4
	s_sub_i32 s3, s3, s14
	v_add_u32_e32 v1, v0, v1
	v_lshlrev_b32_e32 v5, 3, v4
	s_sext_i32_i8 s3, s3
	v_ashrrev_i32_e32 v3, 6, v1
	v_and_b32_e32 v5, -16, v5
	s_add_i32 s60, s5, s3
	v_add_u32_e32 v5, v3, v5
	v_and_b32_e32 v3, 3, v3
	s_ashr_i32 s3, s60, 31
	v_and_or_b32 v3, v5, s46, v3
	s_mul_i32 s3, s62, s3
	s_mul_hi_u32 s5, s62, s60
	s_lshr_b64 s[46:47], s[0:1], 23
	s_sext_i32_i16 s48, s4
	s_add_i32 s3, s5, s3
	s_mul_i32 s5, s46, s60
	s_lshr_b32 s4, s48, 3
	s_add_i32 s5, s3, s5
	s_bfe_i64 s[52:53], s[4:5], 0x100000
	s_ashr_i32 s3, s48, 3
	v_and_b32_e32 v1, 0xc0, v1
	s_mul_hi_u32 s47, s62, s3
	s_mul_i32 s48, s62, s53
	v_lshrrev_b32_e32 v6, 2, v5
	v_lshlrev_b32_e32 v7, 1, v5
	v_sub_u32_e32 v0, v0, v1
	s_add_i32 s47, s47, s48
	s_mul_i32 s46, s46, s3
	v_and_b32_e32 v6, 4, v6
	v_and_b32_e32 v7, 24, v7
	v_lshlrev_b32_e32 v4, 5, v4
	v_ashrrev_i16_sdwa v0, v2, sext(v0) dst_sel:DWORD dst_unused:UNUSED_PAD src0_sel:DWORD src1_sel:BYTE_0
	s_add_i32 s47, s47, s46
	s_mul_i32 s3, s62, s3
	v_readlane_b32 s36, v250, 42
	v_or3_b32 v3, v3, v6, v7
	v_and_b32_e32 v15, 32, v4
	v_bfe_i32 v16, v0, 0, 16
	v_readlane_b32 s37, v250, 43
	s_add_u32 s90, s36, s3
	v_mul_lo_u32 v3, v3, s0
	v_add_u32_e32 v0, v15, v16
	s_addc_u32 s91, s37, s47
	s_add_i32 s3, s8, 0
	v_add_lshl_u32 v132, v3, v0, 1
	s_add_i32 m0, s3, 0x10000
	s_mul_i32 s14, s62, s60
	global_load_lds_dwordx4 v132, s[90:91]
	s_add_i32 m0, s3, 0x12000
	s_add_u32 s64, s90, s10
	global_load_lds_dwordx4 v128, s[90:91]
	s_addc_u32 s65, s91, s11
	s_add_i32 m0, s3, 0x14000
	v_mul_lo_u32 v17, v5, s0
	global_load_lds_dwordx4 v132, s[64:65]
	s_add_i32 m0, s3, 0x16000
	s_add_u32 s88, s9, s14
	s_addc_u32 s89, s15, s5
	s_add_i32 s14, s3, 0x2000
	v_add_lshl_u32 v134, v0, v17, 1
	global_load_lds_dwordx4 v128, s[64:65]
	s_mov_b32 m0, s3
	s_add_u32 s52, s88, s10
	global_load_lds_dwordx4 v134, s[88:89]
	s_mov_b32 m0, s14
	s_addc_u32 s53, s89, s11
	s_add_i32 s46, s3, 0x4000
	global_load_lds_dwordx4 v130, s[88:89]
	s_mov_b32 m0, s46
	s_add_i32 s47, s3, 0x6000
	global_load_lds_dwordx4 v134, s[52:53]
	s_mov_b32 m0, s47
	v_mov_b32_e32 v137, 0
	global_load_lds_dwordx4 v130, s[52:53]
	v_mov_b32_e32 v133, v137
	v_mov_b32_e32 v129, v137
	v_mov_b32_e32 v135, v137
	v_mov_b32_e32 v131, v137
	s_cmp_eq_u32 s54, 1
	s_mov_b32 s52, 0
	v_lshl_add_u64 v[8:9], s[90:91], 0, v[132:133]
	v_lshl_add_u64 v[4:5], s[90:91], 0, v[128:129]
	v_lshl_add_u64 v[2:3], s[64:65], 0, v[132:133]
	v_lshl_add_u64 v[0:1], s[64:65], 0, v[128:129]
	v_lshl_add_u64 v[6:7], s[88:89], 0, v[134:135]
	s_cselect_b64 s[66:67], -1, 0
	s_cmp_lg_u32 s54, 1
	v_lshl_add_u64 v[10:11], s[88:89], 0, v[130:131]
	s_cbranch_scc1 .LBB0_602
	s_barrier

.LBB0_604:
	s_mov_b32 s101, 1
	s_andn2_b64 vcc, exec, s[6:7]
	s_mov_b32 s73, s75
	s_mov_b32 s60, s77
	s_mov_b64 s[90:91], s[86:87]
	s_mov_b64 s[88:89], s[4:5]
	s_cbranch_vccz .LBB0_619

.LBB0_611:
	v_mov_b32_e32 v127, 0
	s_and_b64 vcc, exec, s[0:1]
	v_mov_b32_e32 v126, v127
	v_mov_b32_e32 v125, v127
	v_mov_b32_e32 v124, v127
	v_mov_b32_e32 v123, v127
	v_mov_b32_e32 v122, v127
	v_mov_b32_e32 v121, v127
	v_mov_b32_e32 v120, v127
	v_mov_b32_e32 v111, v127
	v_mov_b32_e32 v110, v127
	v_mov_b32_e32 v109, v127
	v_mov_b32_e32 v108, v127
	v_mov_b32_e32 v107, v127
	v_mov_b32_e32 v106, v127
	v_mov_b32_e32 v105, v127
	v_mov_b32_e32 v104, v127
	v_mov_b32_e32 v95, v127
	v_mov_b32_e32 v94, v127
	v_mov_b32_e32 v93, v127
	v_mov_b32_e32 v92, v127
	v_mov_b32_e32 v91, v127
	v_mov_b32_e32 v90, v127
	v_mov_b32_e32 v89, v127
	v_mov_b32_e32 v88, v127
	v_mov_b32_e32 v79, v127
	v_mov_b32_e32 v78, v127
	v_mov_b32_e32 v77, v127
	v_mov_b32_e32 v76, v127
	v_mov_b32_e32 v75, v127
	v_mov_b32_e32 v74, v127
	v_mov_b32_e32 v73, v127
	v_mov_b32_e32 v72, v127
	v_mov_b32_e32 v119, v127
	v_mov_b32_e32 v118, v127
	v_mov_b32_e32 v117, v127
	v_mov_b32_e32 v116, v127
	v_mov_b32_e32 v115, v127
	v_mov_b32_e32 v114, v127
	v_mov_b32_e32 v113, v127
	v_mov_b32_e32 v112, v127
	v_mov_b32_e32 v103, v127
	v_mov_b32_e32 v102, v127
	v_mov_b32_e32 v101, v127
	v_mov_b32_e32 v100, v127
	v_mov_b32_e32 v99, v127
	v_mov_b32_e32 v98, v127
	v_mov_b32_e32 v97, v127
	v_mov_b32_e32 v96, v127
	v_mov_b32_e32 v87, v127
	v_mov_b32_e32 v86, v127
	v_mov_b32_e32 v85, v127
	v_mov_b32_e32 v84, v127
	v_mov_b32_e32 v83, v127
	v_mov_b32_e32 v82, v127
	v_mov_b32_e32 v81, v127
	v_mov_b32_e32 v80, v127
	v_mov_b32_e32 v71, v127
	v_mov_b32_e32 v70, v127
	v_mov_b32_e32 v69, v127
	v_mov_b32_e32 v68, v127
	v_mov_b32_e32 v67, v127
	v_mov_b32_e32 v66, v127
	v_mov_b32_e32 v65, v127
	v_mov_b32_e32 v64, v127
	v_mov_b32_e32 v63, v127
	v_mov_b32_e32 v62, v127
	v_mov_b32_e32 v61, v127
	v_mov_b32_e32 v60, v127
	v_mov_b32_e32 v59, v127
	v_mov_b32_e32 v58, v127
	v_mov_b32_e32 v57, v127
	v_mov_b32_e32 v56, v127
	v_mov_b32_e32 v47, v127
	v_mov_b32_e32 v46, v127
	v_mov_b32_e32 v45, v127
	v_mov_b32_e32 v44, v127
	v_mov_b32_e32 v43, v127
	v_mov_b32_e32 v42, v127
	v_mov_b32_e32 v41, v127
	v_mov_b32_e32 v40, v127
	v_mov_b32_e32 v31, v127
	v_mov_b32_e32 v30, v127
	v_mov_b32_e32 v29, v127
	v_mov_b32_e32 v28, v127
	v_mov_b32_e32 v27, v127
	v_mov_b32_e32 v26, v127
	v_mov_b32_e32 v25, v127
	v_mov_b32_e32 v24, v127
	v_mov_b32_e32 v15, v127
	v_mov_b32_e32 v14, v127
	v_mov_b32_e32 v13, v127
	v_mov_b32_e32 v12, v127
	v_mov_b32_e32 v11, v127
	v_mov_b32_e32 v10, v127
	v_mov_b32_e32 v9, v127
	v_mov_b32_e32 v8, v127
	v_mov_b32_e32 v55, v127
	v_mov_b32_e32 v54, v127
	v_mov_b32_e32 v53, v127
	v_mov_b32_e32 v52, v127
	v_mov_b32_e32 v51, v127
	v_mov_b32_e32 v50, v127
	v_mov_b32_e32 v49, v127
	v_mov_b32_e32 v48, v127
	v_mov_b32_e32 v39, v127
	v_mov_b32_e32 v38, v127
	v_mov_b32_e32 v37, v127
	v_mov_b32_e32 v36, v127
	v_mov_b32_e32 v35, v127
	v_mov_b32_e32 v34, v127
	v_mov_b32_e32 v33, v127
	v_mov_b32_e32 v32, v127
	v_mov_b32_e32 v23, v127
	v_mov_b32_e32 v22, v127
	v_mov_b32_e32 v21, v127
	v_mov_b32_e32 v20, v127
	v_mov_b32_e32 v19, v127
	v_mov_b32_e32 v18, v127
	v_mov_b32_e32 v17, v127
	v_mov_b32_e32 v16, v127
	v_mov_b32_e32 v7, v127
	v_mov_b32_e32 v6, v127
	v_mov_b32_e32 v5, v127
	v_mov_b32_e32 v4, v127
	v_mov_b32_e32 v3, v127
	v_mov_b32_e32 v2, v127
	v_mov_b32_e32 v1, v127
	v_mov_b32_e32 v0, v127
	s_cbranch_vccnz .LBB0_614
	s_add_u32 s88, s88, 0x80
	s_addc_u32 s89, s89, 0
	s_add_u32 s78, s90, 0x100
	s_addc_u32 s79, s91, 0
	s_mov_b32 s80, 0
	ds_read_b128 v[152:155], v148
	ds_read_b128 v[156:159], v148 offset:1024
	ds_read_b128 v[160:163], v148 offset:2048
	ds_read_b128 v[164:167], v148 offset:3072
	ds_read_b128 v[168:171], v149
	ds_read_b128 v[172:175], v149 offset:1024
	ds_read_b128 v[176:179], v149 offset:2048
	ds_read_b128 v[180:183], v149 offset:3072
	s_add_i32 s81, s80, 2
	s_add_u32 s48, s88, 0x80
	s_addc_u32 s49, s89, 0
	s_cmp_eq_u32 s61, s80
	s_cselect_b32 s91, s5, s49
	s_cselect_b32 s90, s4, s48
	s_cselect_b32 s93, s87, s79
	s_cselect_b32 s92, s86, s78
	s_mov_b32 m0, s70
	v_lshl_add_u64 v[222:223], s[88:89], 0, v[138:139]
	ds_read_b128 v[184:187], v150
	ds_read_b128 v[188:191], v150 offset:1024
	ds_read_b128 v[192:195], v150 offset:2048
	ds_read_b128 v[202:205], v150 offset:3072
	ds_read_b128 v[206:209], v150 offset:4096
	ds_read_b128 v[210:213], v150 offset:5120
	ds_read_b128 v[214:217], v150 offset:6144
	ds_read_b128 v[218:221], v150 offset:7168
	global_load_lds_dwordx4 v[222:223], off
	v_lshl_add_u64 v[222:223], s[88:89], 0, v[140:141]
	s_mov_b32 m0, s71
	s_nop 0
	global_load_lds_dwordx4 v[222:223], off
	s_cmp_eq_u32 s101, 0
	s_cbranch_scc1 .Lqb_ws0
	s_waitcnt vmcnt(24)
	s_branch .Lqb_wd0
.Lqb_ws0:
	s_waitcnt vmcnt(8)
.Lqb_wd0:
	s_waitcnt lgkmcnt(0)
	s_barrier
	s_setprio 1
	s_waitcnt lgkmcnt(0)
	v_mfma_f32_16x16x32_bf16 v[124:127], v[152:155], v[184:187], 0
	v_mfma_f32_16x16x32_bf16 v[120:123], v[160:163], v[184:187], 0
	v_mfma_f32_16x16x32_bf16 v[108:111], v[152:155], v[192:195], 0
	v_mfma_f32_16x16x32_bf16 v[104:107], v[160:163], v[192:195], 0
	v_mfma_f32_16x16x32_bf16 v[92:95], v[152:155], v[206:209], 0
	v_mfma_f32_16x16x32_bf16 v[88:91], v[160:163], v[206:209], 0
	v_mfma_f32_16x16x32_bf16 v[76:79], v[152:155], v[214:217], 0
	v_mfma_f32_16x16x32_bf16 v[72:75], v[160:163], v[214:217], 0
	v_mfma_f32_16x16x32_bf16 v[124:127], v[156:159], v[188:191], v[124:127]
	v_mfma_f32_16x16x32_bf16 v[120:123], v[164:167], v[188:191], v[120:123]
	v_mfma_f32_16x16x32_bf16 v[108:111], v[156:159], v[202:205], v[108:111]
	v_mfma_f32_16x16x32_bf16 v[104:107], v[164:167], v[202:205], v[104:107]
	v_mfma_f32_16x16x32_bf16 v[92:95], v[156:159], v[210:213], v[92:95]
	v_mfma_f32_16x16x32_bf16 v[88:91], v[164:167], v[210:213], v[88:91]
	v_mfma_f32_16x16x32_bf16 v[76:79], v[156:159], v[218:221], v[76:79]
	v_mfma_f32_16x16x32_bf16 v[72:75], v[164:167], v[218:221], v[72:75]
	s_setprio 0
	s_setprio 1
	v_mfma_f32_16x16x32_bf16 v[116:119], v[168:171], v[184:187], 0
	v_mfma_f32_16x16x32_bf16 v[112:115], v[176:179], v[184:187], 0
	v_mfma_f32_16x16x32_bf16 v[100:103], v[168:171], v[192:195], 0
	v_mfma_f32_16x16x32_bf16 v[96:99], v[176:179], v[192:195], 0
	v_mfma_f32_16x16x32_bf16 v[84:87], v[168:171], v[206:209], 0
	v_mfma_f32_16x16x32_bf16 v[80:83], v[176:179], v[206:209], 0
	v_mfma_f32_16x16x32_bf16 v[68:71], v[168:171], v[214:217], 0
	v_mfma_f32_16x16x32_bf16 v[64:67], v[176:179], v[214:217], 0
	v_mfma_f32_16x16x32_bf16 v[116:119], v[172:175], v[188:191], v[116:119]
	v_mfma_f32_16x16x32_bf16 v[112:115], v[180:183], v[188:191], v[112:115]
	v_mfma_f32_16x16x32_bf16 v[100:103], v[172:175], v[202:205], v[100:103]
	v_mfma_f32_16x16x32_bf16 v[96:99], v[180:183], v[202:205], v[96:99]
	v_mfma_f32_16x16x32_bf16 v[84:87], v[172:175], v[210:213], v[84:87]
	v_mfma_f32_16x16x32_bf16 v[80:83], v[180:183], v[210:213], v[80:83]
	v_mfma_f32_16x16x32_bf16 v[68:71], v[172:175], v[218:221], v[68:71]
	v_mfma_f32_16x16x32_bf16 v[64:67], v[180:183], v[218:221], v[64:67]
	s_setprio 0
	s_barrier
	s_mov_b32 m0, s72
	v_lshl_add_u64 v[222:223], s[92:93], 0, v[132:133]
	ds_read_b128 v[184:187], v150 offset:16384
	ds_read_b128 v[188:191], v150 offset:17408
	ds_read_b128 v[192:195], v150 offset:18432
	ds_read_b128 v[202:205], v150 offset:19456
	ds_read_b128 v[206:209], v150 offset:20480
	ds_read_b128 v[210:213], v150 offset:21504
	ds_read_b128 v[214:217], v150 offset:22528
	ds_read_b128 v[218:221], v150 offset:23552
	global_load_lds_dwordx4 v[222:223], off
	s_add_i32 m0, s72, 0x2000
	v_lshl_add_u64 v[224:225], s[92:93], 0, v[128:129]
	s_add_u32 s92, s92, s10
	s_addc_u32 s93, s93, s11
	s_add_i32 s48, s64, s8
	global_load_lds_dwordx4 v[224:225], off
	v_lshl_add_u64 v[226:227], s[92:93], 0, v[132:133]
	s_mov_b32 m0, s48
	v_lshl_add_u64 v[228:229], s[92:93], 0, v[128:129]
	global_load_lds_dwordx4 v[226:227], off
	s_add_i32 m0, s48, 0x2000
	v_lshl_add_u64 v[230:231], s[90:91], 0, v[134:135]
	global_load_lds_dwordx4 v[228:229], off
	s_mov_b32 m0, s3
	v_lshl_add_u64 v[232:233], s[90:91], 0, v[130:131]
	global_load_lds_dwordx4 v[230:231], off
	s_mov_b32 m0, s14
	s_nop 0
	global_load_lds_dwordx4 v[232:233], off
	s_cmp_eq_u32 s101, 0
	s_cbranch_scc1 .Lqb_ws1
	s_waitcnt vmcnt(24)
	s_branch .Lqb_wd1

.Lqb_wd1:
	s_waitcnt lgkmcnt(0)
	s_barrier
	s_setprio 1
	s_waitcnt lgkmcnt(0)
	v_mfma_f32_16x16x32_bf16 v[60:63], v[152:155], v[184:187], 0
	v_mfma_f32_16x16x32_bf16 v[56:59], v[160:163], v[184:187], 0
	v_mfma_f32_16x16x32_bf16 v[44:47], v[152:155], v[192:195], 0
	v_mfma_f32_16x16x32_bf16 v[40:43], v[160:163], v[192:195], 0
	v_mfma_f32_16x16x32_bf16 v[28:31], v[152:155], v[206:209], 0
	v_mfma_f32_16x16x32_bf16 v[24:27], v[160:163], v[206:209], 0
	v_mfma_f32_16x16x32_bf16 v[12:15], v[152:155], v[214:217], 0
	v_mfma_f32_16x16x32_bf16 v[8:11], v[160:163], v[214:217], 0
	v_mfma_f32_16x16x32_bf16 v[60:63], v[156:159], v[188:191], v[60:63]
	v_mfma_f32_16x16x32_bf16 v[56:59], v[164:167], v[188:191], v[56:59]
	v_mfma_f32_16x16x32_bf16 v[44:47], v[156:159], v[202:205], v[44:47]
	v_mfma_f32_16x16x32_bf16 v[40:43], v[164:167], v[202:205], v[40:43]
	v_mfma_f32_16x16x32_bf16 v[28:31], v[156:159], v[210:213], v[28:31]
	v_mfma_f32_16x16x32_bf16 v[24:27], v[164:167], v[210:213], v[24:27]
	v_mfma_f32_16x16x32_bf16 v[12:15], v[156:159], v[218:221], v[12:15]
	v_mfma_f32_16x16x32_bf16 v[8:11], v[164:167], v[218:221], v[8:11]
	s_setprio 0
	s_setprio 1
	v_mfma_f32_16x16x32_bf16 v[52:55], v[168:171], v[184:187], 0
	v_mfma_f32_16x16x32_bf16 v[48:51], v[176:179], v[184:187], 0
	v_mfma_f32_16x16x32_bf16 v[36:39], v[168:171], v[192:195], 0
	v_mfma_f32_16x16x32_bf16 v[32:35], v[176:179], v[192:195], 0
	v_mfma_f32_16x16x32_bf16 v[20:23], v[168:171], v[206:209], 0
	v_mfma_f32_16x16x32_bf16 v[16:19], v[176:179], v[206:209], 0
	v_mfma_f32_16x16x32_bf16 v[4:7], v[168:171], v[214:217], 0
	v_mfma_f32_16x16x32_bf16 v[0:3], v[176:179], v[214:217], 0
	v_mfma_f32_16x16x32_bf16 v[52:55], v[172:175], v[188:191], v[52:55]
	v_mfma_f32_16x16x32_bf16 v[48:51], v[180:183], v[188:191], v[48:51]
	v_mfma_f32_16x16x32_bf16 v[36:39], v[172:175], v[202:205], v[36:39]
	v_mfma_f32_16x16x32_bf16 v[32:35], v[180:183], v[202:205], v[32:35]
	v_mfma_f32_16x16x32_bf16 v[20:23], v[172:175], v[210:213], v[20:23]
	v_mfma_f32_16x16x32_bf16 v[16:19], v[180:183], v[210:213], v[16:19]
	v_mfma_f32_16x16x32_bf16 v[4:7], v[172:175], v[218:221], v[4:7]
	v_mfma_f32_16x16x32_bf16 v[0:3], v[180:183], v[218:221], v[0:3]
	s_setprio 0
	s_barrier
	s_add_i32 s48, 0, 0x18000
	v_add_u32_e32 v151, s48, v147
	s_add_i32 s49, 0, 0x1c000
	ds_read_b128 v[152:155], v151
	ds_read_b128 v[156:159], v151 offset:1024
	ds_read_b128 v[160:163], v151 offset:2048
	ds_read_b128 v[164:167], v151 offset:3072
	v_add_u32_e32 v151, s49, v147
	ds_read_b128 v[168:171], v151
	ds_read_b128 v[172:175], v151 offset:1024
	ds_read_b128 v[176:179], v151 offset:2048
	ds_read_b128 v[180:183], v151 offset:3072
	s_add_u32 s90, s90, s10
	s_addc_u32 s91, s91, s11
	s_mov_b32 m0, s46
	v_lshl_add_u64 v[234:235], s[90:91], 0, v[134:135]
	ds_read_b128 v[184:187], v150 offset:32768
	ds_read_b128 v[188:191], v150 offset:33792
	ds_read_b128 v[192:195], v150 offset:34816
	ds_read_b128 v[202:205], v150 offset:35840
	ds_read_b128 v[206:209], v150 offset:36864
	ds_read_b128 v[210:213], v150 offset:37888
	ds_read_b128 v[214:217], v150 offset:38912
	ds_read_b128 v[218:221], v150 offset:39936
	global_load_lds_dwordx4 v[234:235], off
	v_lshl_add_u64 v[234:235], s[90:91], 0, v[130:131]
	s_mov_b32 m0, s47
	s_nop 0
	global_load_lds_dwordx4 v[234:235], off
	s_waitcnt vmcnt(8)
	s_waitcnt lgkmcnt(0)
	s_barrier
	s_setprio 1
	s_waitcnt lgkmcnt(0)
	v_mfma_f32_16x16x32_bf16 v[124:127], v[152:155], v[184:187], v[124:127]
	v_mfma_f32_16x16x32_bf16 v[120:123], v[160:163], v[184:187], v[120:123]
	v_mfma_f32_16x16x32_bf16 v[108:111], v[152:155], v[192:195], v[108:111]
	v_mfma_f32_16x16x32_bf16 v[104:107], v[160:163], v[192:195], v[104:107]
	v_mfma_f32_16x16x32_bf16 v[92:95], v[152:155], v[206:209], v[92:95]
	v_mfma_f32_16x16x32_bf16 v[88:91], v[160:163], v[206:209], v[88:91]
	v_mfma_f32_16x16x32_bf16 v[76:79], v[152:155], v[214:217], v[76:79]
	v_mfma_f32_16x16x32_bf16 v[72:75], v[160:163], v[214:217], v[72:75]
	v_mfma_f32_16x16x32_bf16 v[124:127], v[156:159], v[188:191], v[124:127]
	v_mfma_f32_16x16x32_bf16 v[120:123], v[164:167], v[188:191], v[120:123]
	v_mfma_f32_16x16x32_bf16 v[108:111], v[156:159], v[202:205], v[108:111]
	v_mfma_f32_16x16x32_bf16 v[104:107], v[164:167], v[202:205], v[104:107]
	v_mfma_f32_16x16x32_bf16 v[92:95], v[156:159], v[210:213], v[92:95]
	v_mfma_f32_16x16x32_bf16 v[88:91], v[164:167], v[210:213], v[88:91]
	v_mfma_f32_16x16x32_bf16 v[76:79], v[156:159], v[218:221], v[76:79]
	v_mfma_f32_16x16x32_bf16 v[72:75], v[164:167], v[218:221], v[72:75]
	s_setprio 0
	s_setprio 1
	v_mfma_f32_16x16x32_bf16 v[116:119], v[168:171], v[184:187], v[116:119]
	v_mfma_f32_16x16x32_bf16 v[112:115], v[176:179], v[184:187], v[112:115]
	v_mfma_f32_16x16x32_bf16 v[100:103], v[168:171], v[192:195], v[100:103]
	v_mfma_f32_16x16x32_bf16 v[96:99], v[176:179], v[192:195], v[96:99]
	v_mfma_f32_16x16x32_bf16 v[84:87], v[168:171], v[206:209], v[84:87]
	v_mfma_f32_16x16x32_bf16 v[80:83], v[176:179], v[206:209], v[80:83]
	v_mfma_f32_16x16x32_bf16 v[68:71], v[168:171], v[214:217], v[68:71]
	v_mfma_f32_16x16x32_bf16 v[64:67], v[176:179], v[214:217], v[64:67]
	v_mfma_f32_16x16x32_bf16 v[116:119], v[172:175], v[188:191], v[116:119]
	v_mfma_f32_16x16x32_bf16 v[112:115], v[180:183], v[188:191], v[112:115]
	v_mfma_f32_16x16x32_bf16 v[100:103], v[172:175], v[202:205], v[100:103]
	v_mfma_f32_16x16x32_bf16 v[96:99], v[180:183], v[202:205], v[96:99]
	v_mfma_f32_16x16x32_bf16 v[84:87], v[172:175], v[210:213], v[84:87]
	v_mfma_f32_16x16x32_bf16 v[80:83], v[180:183], v[210:213], v[80:83]
	v_mfma_f32_16x16x32_bf16 v[68:71], v[172:175], v[218:221], v[68:71]
	v_mfma_f32_16x16x32_bf16 v[64:67], v[180:183], v[218:221], v[64:67]
	s_setprio 0
	s_barrier
	s_add_i32 s48, s48, s8
	v_lshl_add_u64 v[222:223], v[222:223], 0, s[82:83]
	s_mov_b32 m0, s48
	ds_read_b128 v[184:187], v150 offset:49152
	ds_read_b128 v[188:191], v150 offset:50176
	ds_read_b128 v[192:195], v150 offset:51200
	ds_read_b128 v[202:205], v150 offset:52224
	ds_read_b128 v[206:209], v150 offset:53248
	ds_read_b128 v[210:213], v150 offset:54272
	ds_read_b128 v[214:217], v150 offset:55296
	ds_read_b128 v[218:221], v150 offset:56320
	global_load_lds_dwordx4 v[222:223], off
	v_lshl_add_u64 v[222:223], v[224:225], 0, s[82:83]
	s_add_i32 m0, s48, 0x2000
	s_add_i32 s48, s49, s8
	global_load_lds_dwordx4 v[222:223], off
	v_lshl_add_u64 v[222:223], v[226:227], 0, s[82:83]
	s_mov_b32 m0, s48
	s_nop 0
	global_load_lds_dwordx4 v[222:223], off
	v_lshl_add_u64 v[222:223], v[228:229], 0, s[82:83]
	s_add_i32 m0, s48, 0x2000
	s_nop 0
	global_load_lds_dwordx4 v[222:223], off
	v_lshl_add_u64 v[222:223], v[230:231], 0, s[82:83]
	s_mov_b32 m0, s54
	s_nop 0
	global_load_lds_dwordx4 v[222:223], off
	v_lshl_add_u64 v[222:223], v[232:233], 0, s[82:83]
	s_mov_b32 m0, s55
	s_nop 0
	global_load_lds_dwordx4 v[222:223], off
	s_waitcnt vmcnt(8)
	s_waitcnt lgkmcnt(0)
	s_barrier
	s_setprio 1
	s_waitcnt lgkmcnt(0)
	v_mfma_f32_16x16x32_bf16 v[60:63], v[152:155], v[184:187], v[60:63]
	v_mfma_f32_16x16x32_bf16 v[56:59], v[160:163], v[184:187], v[56:59]
	v_mfma_f32_16x16x32_bf16 v[44:47], v[152:155], v[192:195], v[44:47]
	v_mfma_f32_16x16x32_bf16 v[40:43], v[160:163], v[192:195], v[40:43]
	v_mfma_f32_16x16x32_bf16 v[28:31], v[152:155], v[206:209], v[28:31]
	v_mfma_f32_16x16x32_bf16 v[24:27], v[160:163], v[206:209], v[24:27]
	v_mfma_f32_16x16x32_bf16 v[12:15], v[152:155], v[214:217], v[12:15]
	v_mfma_f32_16x16x32_bf16 v[8:11], v[160:163], v[214:217], v[8:11]
	v_mfma_f32_16x16x32_bf16 v[60:63], v[156:159], v[188:191], v[60:63]
	v_mfma_f32_16x16x32_bf16 v[56:59], v[164:167], v[188:191], v[56:59]
	v_mfma_f32_16x16x32_bf16 v[44:47], v[156:159], v[202:205], v[44:47]
	v_mfma_f32_16x16x32_bf16 v[40:43], v[164:167], v[202:205], v[40:43]
	v_mfma_f32_16x16x32_bf16 v[28:31], v[156:159], v[210:213], v[28:31]
	v_mfma_f32_16x16x32_bf16 v[24:27], v[164:167], v[210:213], v[24:27]
	v_mfma_f32_16x16x32_bf16 v[12:15], v[156:159], v[218:221], v[12:15]
	v_mfma_f32_16x16x32_bf16 v[8:11], v[164:167], v[218:221], v[8:11]
	s_setprio 0
	s_setprio 1
	v_mfma_f32_16x16x32_bf16 v[52:55], v[168:171], v[184:187], v[52:55]
	v_mfma_f32_16x16x32_bf16 v[48:51], v[176:179], v[184:187], v[48:51]
	v_mfma_f32_16x16x32_bf16 v[36:39], v[168:171], v[192:195], v[36:39]
	v_mfma_f32_16x16x32_bf16 v[32:35], v[176:179], v[192:195], v[32:35]
	v_mfma_f32_16x16x32_bf16 v[20:23], v[168:171], v[206:209], v[20:23]
	v_mfma_f32_16x16x32_bf16 v[16:19], v[176:179], v[206:209], v[16:19]
	v_mfma_f32_16x16x32_bf16 v[4:7], v[168:171], v[214:217], v[4:7]
	v_mfma_f32_16x16x32_bf16 v[0:3], v[176:179], v[214:217], v[0:3]
	v_mfma_f32_16x16x32_bf16 v[52:55], v[172:175], v[188:191], v[52:55]
	v_mfma_f32_16x16x32_bf16 v[48:51], v[180:183], v[188:191], v[48:51]
	v_mfma_f32_16x16x32_bf16 v[36:39], v[172:175], v[202:205], v[36:39]
	v_mfma_f32_16x16x32_bf16 v[32:35], v[180:183], v[202:205], v[32:35]
	v_mfma_f32_16x16x32_bf16 v[20:23], v[172:175], v[210:213], v[20:23]
	v_mfma_f32_16x16x32_bf16 v[16:19], v[180:183], v[210:213], v[16:19]
	v_mfma_f32_16x16x32_bf16 v[4:7], v[172:175], v[218:221], v[4:7]
	v_mfma_f32_16x16x32_bf16 v[0:3], v[180:183], v[218:221], v[0:3]
	s_setprio 0
	s_barrier
	s_add_u32 s88, s88, 0x100
	s_addc_u32 s89, s89, 0
	s_add_u32 s78, s78, 0x100
	s_addc_u32 s79, s79, 0
	s_cmp_ge_i32 s81, s53
	s_mov_b32 s80, s81
